# S3 epilogue rewritten: tanh-gelu with packed f32 math (v_pk_mul/fma/add_f32, folded constants, f32 throughout), addresses hoisted; on top of zearly
# speedup vs baseline: 1.0599x; 1.0006x over previous
; __device__ __forceinline__ unsigned cvt_pk_bf16(float lo, float hi) { unsigned r; asm volatile("v_cvt_pk_bf16_f32 %0, %1, %2" : "=v"(r) : "v"(lo), "v"(hi)); return r; }
; __device__ __forceinline__ float gelu_tanh_f(float y) { const float t = 0.7978845608028654f * (y + 0.044715f * y * y * y); return y * sigmoid_f(2.0f * t); }
;     __device__ __forceinline__ void operator()(const AccT& acc, const Unit& u, int wr, int wc, int fr, int fq) const {
; #pragma unroll
;         for (int ai = 0; ai < 2; ++ai)
; #pragma unroll
;             for (int m = 0; m < 4; ++m) {
;                 const int rg = u.pm * 256 + ai * 128 + wr * 64 + m * 16 + fr;
; #pragma unroll
;                 for (int bj = 0; bj < 2; ++bj) {
;                     const int nc = u.pn * 256 + bj * 128 + wc * 32 + 8 * fq, i = nc >> 4, s0 = nc & 15;
;                     const f32x4 v0 = acc[ai][bj][m][0], v1 = acc[ai][bj][m][1];
;                     u32x4 w; w.x = cvt_pk_bf16(gelu_tanh_f(v0[0]), gelu_tanh_f(v0[1])); w.y = cvt_pk_bf16(gelu_tanh_f(v0[2]), gelu_tanh_f(v0[3]));
;                     w.z = cvt_pk_bf16(gelu_tanh_f(v1[0]), gelu_tanh_f(v1[1])); w.w = cvt_pk_bf16(gelu_tanh_f(v1[2]), gelu_tanh_f(v1[3]));
;                     *(u32x4*)(YG + ((size_t)rg * 32 + i) * 1024 + u.g * 16 + s0) = w;
;                 }
;             }
;     }
.LBB0_537:
	v_mov_b32_e32 v160, 0xc0135761
	v_mov_b32_e32 v161, 0xc0135761
	v_mov_b32_e32 v162, 0xbdd2d3e7
	v_mov_b32_e32 v163, 0xbdd2d3e7
	s_lshl_b32 s24, s89, 8
	s_lshl_b32 s22, s37, 4
	s_ashr_i32 s23, s22, 31
	s_lshl_b64 s[22:23], s[22:23], 1
	v_lshl_or_b32 v172, s38, 8, v153
	v_ashrrev_i32_e32 v172, 4, v172
	v_or_b32_e32 v174, 8, v172
	v_ashrrev_i32_e32 v173, 31, v172
	v_lshlrev_b64 v[172:173], 11, v[172:173]
	v_lshl_add_u64 v[172:173], s[8:9], 0, v[172:173]
	v_lshl_add_u64 v[172:173], v[172:173], 0, s[22:23]
	v_lshl_add_u64 v[172:173], v[172:173], 0, v[224:225]
	v_ashrrev_i32_e32 v175, 31, v174
	v_lshlrev_b64 v[174:175], 11, v[174:175]
	v_lshl_add_u64 v[174:175], s[8:9], 0, v[174:175]
	v_lshl_add_u64 v[174:175], v[174:175], 0, s[22:23]
	v_lshl_add_u64 v[174:175], v[174:175], 0, v[224:225]
	v_pk_mul_f32 v[164:165], v[124:125], v[124:125]
	v_pk_mul_f32 v[166:167], v[126:127], v[126:127]
	v_pk_mul_f32 v[168:169], v[120:121], v[120:121]
	v_pk_mul_f32 v[170:171], v[122:123], v[122:123]
	v_pk_fma_f32 v[164:165], v[164:165], v[162:163], v[160:161]
	v_pk_fma_f32 v[166:167], v[166:167], v[162:163], v[160:161]
	v_pk_fma_f32 v[168:169], v[168:169], v[162:163], v[160:161]
	v_pk_fma_f32 v[170:171], v[170:171], v[162:163], v[160:161]
	v_pk_mul_f32 v[164:165], v[164:165], v[124:125]
	v_pk_mul_f32 v[166:167], v[166:167], v[126:127]
	v_pk_mul_f32 v[168:169], v[168:169], v[120:121]
	v_pk_mul_f32 v[170:171], v[170:171], v[122:123]
	v_exp_f32_e32 v164, v164
	v_exp_f32_e32 v165, v165
	v_exp_f32_e32 v166, v166
	v_exp_f32_e32 v167, v167
	v_exp_f32_e32 v168, v168
	v_exp_f32_e32 v169, v169
	v_exp_f32_e32 v170, v170
	v_exp_f32_e32 v171, v171
	v_add_u32_e32 v176, s24, v144
	v_ashrrev_i32_e32 v177, 31, v176
	v_lshlrev_b64 v[176:177], 16, v[176:177]
	v_lshl_add_u64 v[178:179], v[176:177], 0, v[172:173]
	v_lshl_add_u64 v[180:181], v[176:177], 0, v[174:175]
	v_pk_add_f32 v[164:165], v[164:165], 1.0 op_sel_hi:[1,0]
	v_pk_add_f32 v[166:167], v[166:167], 1.0 op_sel_hi:[1,0]
	v_pk_add_f32 v[168:169], v[168:169], 1.0 op_sel_hi:[1,0]
	v_pk_add_f32 v[170:171], v[170:171], 1.0 op_sel_hi:[1,0]
	v_rcp_f32_e32 v164, v164
	v_rcp_f32_e32 v165, v165
	v_rcp_f32_e32 v166, v166
	v_rcp_f32_e32 v167, v167
	v_rcp_f32_e32 v168, v168
	v_rcp_f32_e32 v169, v169
	v_rcp_f32_e32 v170, v170
	v_rcp_f32_e32 v171, v171
	v_pk_mul_f32 v[124:125], v[124:125], v[164:165]
	v_pk_mul_f32 v[126:127], v[126:127], v[166:167]
	v_pk_mul_f32 v[120:121], v[120:121], v[168:169]
	v_pk_mul_f32 v[122:123], v[122:123], v[170:171]
	v_cvt_pk_bf16_f32 v124, v124, v125
	v_cvt_pk_bf16_f32 v125, v126, v127
	v_cvt_pk_bf16_f32 v126, v120, v121
	v_cvt_pk_bf16_f32 v127, v122, v123
	global_store_dwordx4 v[178:179], v[124:127], off
	v_pk_mul_f32 v[164:165], v[116:117], v[116:117]
	v_pk_mul_f32 v[166:167], v[118:119], v[118:119]
	v_pk_mul_f32 v[168:169], v[112:113], v[112:113]
	v_pk_mul_f32 v[170:171], v[114:115], v[114:115]
	v_pk_fma_f32 v[164:165], v[164:165], v[162:163], v[160:161]
	v_pk_fma_f32 v[166:167], v[166:167], v[162:163], v[160:161]
	v_pk_fma_f32 v[168:169], v[168:169], v[162:163], v[160:161]
	v_pk_fma_f32 v[170:171], v[170:171], v[162:163], v[160:161]
	v_pk_mul_f32 v[164:165], v[164:165], v[116:117]
	v_pk_mul_f32 v[166:167], v[166:167], v[118:119]
	v_pk_mul_f32 v[168:169], v[168:169], v[112:113]
	v_pk_mul_f32 v[170:171], v[170:171], v[114:115]
	v_exp_f32_e32 v164, v164
	v_exp_f32_e32 v165, v165
	v_exp_f32_e32 v166, v166
	v_exp_f32_e32 v167, v167
	v_exp_f32_e32 v168, v168
	v_exp_f32_e32 v169, v169
	v_exp_f32_e32 v170, v170
	v_exp_f32_e32 v171, v171
	v_pk_add_f32 v[164:165], v[164:165], 1.0 op_sel_hi:[1,0]
	v_pk_add_f32 v[166:167], v[166:167], 1.0 op_sel_hi:[1,0]
	v_pk_add_f32 v[168:169], v[168:169], 1.0 op_sel_hi:[1,0]
	v_pk_add_f32 v[170:171], v[170:171], 1.0 op_sel_hi:[1,0]
	v_rcp_f32_e32 v164, v164
	v_rcp_f32_e32 v165, v165
	v_rcp_f32_e32 v166, v166
	v_rcp_f32_e32 v167, v167
	v_rcp_f32_e32 v168, v168
	v_rcp_f32_e32 v169, v169
	v_rcp_f32_e32 v170, v170
	v_rcp_f32_e32 v171, v171
	v_pk_mul_f32 v[116:117], v[116:117], v[164:165]
	v_pk_mul_f32 v[118:119], v[118:119], v[166:167]
	v_pk_mul_f32 v[112:113], v[112:113], v[168:169]
	v_pk_mul_f32 v[114:115], v[114:115], v[170:171]
	v_cvt_pk_bf16_f32 v116, v116, v117
	v_cvt_pk_bf16_f32 v117, v118, v119
	v_cvt_pk_bf16_f32 v118, v112, v113
	v_cvt_pk_bf16_f32 v119, v114, v115
	global_store_dwordx4 v[180:181], v[116:119], off
	v_pk_mul_f32 v[164:165], v[108:109], v[108:109]
	v_pk_mul_f32 v[166:167], v[110:111], v[110:111]
	v_pk_mul_f32 v[168:169], v[104:105], v[104:105]
	v_pk_mul_f32 v[170:171], v[106:107], v[106:107]
	v_pk_fma_f32 v[164:165], v[164:165], v[162:163], v[160:161]
	v_pk_fma_f32 v[166:167], v[166:167], v[162:163], v[160:161]
	v_pk_fma_f32 v[168:169], v[168:169], v[162:163], v[160:161]
	v_pk_fma_f32 v[170:171], v[170:171], v[162:163], v[160:161]
	v_pk_mul_f32 v[164:165], v[164:165], v[108:109]
	v_pk_mul_f32 v[166:167], v[166:167], v[110:111]
	v_pk_mul_f32 v[168:169], v[168:169], v[104:105]
	v_pk_mul_f32 v[170:171], v[170:171], v[106:107]
	v_exp_f32_e32 v164, v164
	v_exp_f32_e32 v165, v165
	v_exp_f32_e32 v166, v166
	v_exp_f32_e32 v167, v167
	v_exp_f32_e32 v168, v168
	v_exp_f32_e32 v169, v169
	v_exp_f32_e32 v170, v170
	v_exp_f32_e32 v171, v171
	v_add_u32_e32 v176, s24, v146
	v_ashrrev_i32_e32 v177, 31, v176
	v_lshlrev_b64 v[176:177], 16, v[176:177]
	v_lshl_add_u64 v[178:179], v[176:177], 0, v[172:173]
	v_lshl_add_u64 v[180:181], v[176:177], 0, v[174:175]
	v_pk_add_f32 v[164:165], v[164:165], 1.0 op_sel_hi:[1,0]
	v_pk_add_f32 v[166:167], v[166:167], 1.0 op_sel_hi:[1,0]
	v_pk_add_f32 v[168:169], v[168:169], 1.0 op_sel_hi:[1,0]
	v_pk_add_f32 v[170:171], v[170:171], 1.0 op_sel_hi:[1,0]
; __device__ __forceinline__ unsigned cvt_pk_bf16(float lo, float hi) { unsigned r; asm volatile("v_cvt_pk_bf16_f32 %0, %1, %2" : "=v"(r) : "v"(lo), "v"(hi)); return r; }
; __device__ __forceinline__ float gelu_tanh_f(float y) { const float t = 0.7978845608028654f * (y + 0.044715f * y * y * y); return y * sigmoid_f(2.0f * t); }
; __device__ __forceinline__ float silu_f(float z) { return z / (1.0f + __expf(-z)); }
; __device__ __forceinline__ float sigmoid_f(float z) { return 1.0f / (1.0f + __expf(-z)); }
;     __device__ __forceinline__ void operator()(const AccT& acc, const Unit& u, int wr, int wc, int fr, int fq) const {
;     ...
;                 for (int bj = 0; bj < 2; ++bj) {
;                     const int nc = u.pn * 256 + bj * 128 + wc * 32 + 8 * fq, i = nc >> 4, s0 = nc & 15;
;                     const f32x4 v0 = acc[ai][bj][m][0], v1 = acc[ai][bj][m][1];
;                     u32x4 w; w.x = cvt_pk_bf16(gelu_tanh_f(v0[0]), gelu_tanh_f(v0[1])); w.y = cvt_pk_bf16(gelu_tanh_f(v0[2]), gelu_tanh_f(v0[3]));
;                     w.z = cvt_pk_bf16(gelu_tanh_f(v1[0]), gelu_tanh_f(v1[1])); w.w = cvt_pk_bf16(gelu_tanh_f(v1[2]), gelu_tanh_f(v1[3]));
;                     *(u32x4*)(YG + ((size_t)rg * 32 + i) * 1024 + u.g * 16 + s0) = w;
	v_rcp_f32_e32 v164, v164
	v_rcp_f32_e32 v165, v165
	v_rcp_f32_e32 v166, v166
	v_rcp_f32_e32 v167, v167
	v_rcp_f32_e32 v168, v168
	v_rcp_f32_e32 v169, v169
	v_rcp_f32_e32 v170, v170
	v_rcp_f32_e32 v171, v171
	v_pk_mul_f32 v[108:109], v[108:109], v[164:165]
	v_pk_mul_f32 v[110:111], v[110:111], v[166:167]
	v_pk_mul_f32 v[104:105], v[104:105], v[168:169]
	v_pk_mul_f32 v[106:107], v[106:107], v[170:171]
	v_cvt_pk_bf16_f32 v108, v108, v109
	v_cvt_pk_bf16_f32 v109, v110, v111
	v_cvt_pk_bf16_f32 v110, v104, v105
	v_cvt_pk_bf16_f32 v111, v106, v107
	global_store_dwordx4 v[178:179], v[108:111], off
	v_pk_mul_f32 v[164:165], v[100:101], v[100:101]
	v_pk_mul_f32 v[166:167], v[102:103], v[102:103]
	v_pk_mul_f32 v[168:169], v[96:97], v[96:97]
	v_pk_mul_f32 v[170:171], v[98:99], v[98:99]
	v_pk_fma_f32 v[164:165], v[164:165], v[162:163], v[160:161]
	v_pk_fma_f32 v[166:167], v[166:167], v[162:163], v[160:161]
	v_pk_fma_f32 v[168:169], v[168:169], v[162:163], v[160:161]
	v_pk_fma_f32 v[170:171], v[170:171], v[162:163], v[160:161]
	v_pk_mul_f32 v[164:165], v[164:165], v[100:101]
	v_pk_mul_f32 v[166:167], v[166:167], v[102:103]
	v_pk_mul_f32 v[168:169], v[168:169], v[96:97]
	v_pk_mul_f32 v[170:171], v[170:171], v[98:99]
	v_exp_f32_e32 v164, v164
	v_exp_f32_e32 v165, v165
	v_exp_f32_e32 v166, v166
	v_exp_f32_e32 v167, v167
	v_exp_f32_e32 v168, v168
	v_exp_f32_e32 v169, v169
	v_exp_f32_e32 v170, v170
	v_exp_f32_e32 v171, v171
	v_pk_add_f32 v[164:165], v[164:165], 1.0 op_sel_hi:[1,0]
	v_pk_add_f32 v[166:167], v[166:167], 1.0 op_sel_hi:[1,0]
	v_pk_add_f32 v[168:169], v[168:169], 1.0 op_sel_hi:[1,0]
	v_pk_add_f32 v[170:171], v[170:171], 1.0 op_sel_hi:[1,0]
	v_rcp_f32_e32 v164, v164
	v_rcp_f32_e32 v165, v165
	v_rcp_f32_e32 v166, v166
	v_rcp_f32_e32 v167, v167
	v_rcp_f32_e32 v168, v168
	v_rcp_f32_e32 v169, v169
	v_rcp_f32_e32 v170, v170
	v_rcp_f32_e32 v171, v171
	v_pk_mul_f32 v[100:101], v[100:101], v[164:165]
	v_pk_mul_f32 v[102:103], v[102:103], v[166:167]
	v_pk_mul_f32 v[96:97], v[96:97], v[168:169]
	v_pk_mul_f32 v[98:99], v[98:99], v[170:171]
	v_cvt_pk_bf16_f32 v100, v100, v101
	v_cvt_pk_bf16_f32 v101, v102, v103
	v_cvt_pk_bf16_f32 v102, v96, v97
	v_cvt_pk_bf16_f32 v103, v98, v99
	global_store_dwordx4 v[180:181], v[100:103], off
	v_pk_mul_f32 v[164:165], v[92:93], v[92:93]
	v_pk_mul_f32 v[166:167], v[94:95], v[94:95]
	v_pk_mul_f32 v[168:169], v[88:89], v[88:89]
	v_pk_mul_f32 v[170:171], v[90:91], v[90:91]
	v_pk_fma_f32 v[164:165], v[164:165], v[162:163], v[160:161]
	v_pk_fma_f32 v[166:167], v[166:167], v[162:163], v[160:161]
	v_pk_fma_f32 v[168:169], v[168:169], v[162:163], v[160:161]
	v_pk_fma_f32 v[170:171], v[170:171], v[162:163], v[160:161]
	v_pk_mul_f32 v[164:165], v[164:165], v[92:93]
	v_pk_mul_f32 v[166:167], v[166:167], v[94:95]
	v_pk_mul_f32 v[168:169], v[168:169], v[88:89]
	v_pk_mul_f32 v[170:171], v[170:171], v[90:91]
	v_exp_f32_e32 v164, v164
	v_exp_f32_e32 v165, v165
	v_exp_f32_e32 v166, v166
	v_exp_f32_e32 v167, v167
	v_exp_f32_e32 v168, v168
	v_exp_f32_e32 v169, v169
	v_exp_f32_e32 v170, v170
	v_exp_f32_e32 v171, v171
	v_add_u32_e32 v176, s24, v147
	v_ashrrev_i32_e32 v177, 31, v176
	v_lshlrev_b64 v[176:177], 16, v[176:177]
	v_lshl_add_u64 v[178:179], v[176:177], 0, v[172:173]
	v_lshl_add_u64 v[180:181], v[176:177], 0, v[174:175]
	v_pk_add_f32 v[164:165], v[164:165], 1.0 op_sel_hi:[1,0]
	v_pk_add_f32 v[166:167], v[166:167], 1.0 op_sel_hi:[1,0]
	v_pk_add_f32 v[168:169], v[168:169], 1.0 op_sel_hi:[1,0]
	v_pk_add_f32 v[170:171], v[170:171], 1.0 op_sel_hi:[1,0]
	v_rcp_f32_e32 v164, v164
	v_rcp_f32_e32 v165, v165
	v_rcp_f32_e32 v166, v166
	v_rcp_f32_e32 v167, v167
	v_rcp_f32_e32 v168, v168
	v_rcp_f32_e32 v169, v169
	v_rcp_f32_e32 v170, v170
	v_rcp_f32_e32 v171, v171
	v_pk_mul_f32 v[92:93], v[92:93], v[164:165]
	v_pk_mul_f32 v[94:95], v[94:95], v[166:167]
	v_pk_mul_f32 v[88:89], v[88:89], v[168:169]
	v_pk_mul_f32 v[90:91], v[90:91], v[170:171]
	v_cvt_pk_bf16_f32 v92, v92, v93
	v_cvt_pk_bf16_f32 v93, v94, v95
	v_cvt_pk_bf16_f32 v94, v88, v89
	v_cvt_pk_bf16_f32 v95, v90, v91
	global_store_dwordx4 v[178:179], v[92:95], off
	v_pk_mul_f32 v[164:165], v[84:85], v[84:85]
	v_pk_mul_f32 v[166:167], v[86:87], v[86:87]
	v_pk_mul_f32 v[168:169], v[80:81], v[80:81]
	v_pk_mul_f32 v[170:171], v[82:83], v[82:83]
	v_pk_fma_f32 v[164:165], v[164:165], v[162:163], v[160:161]
	v_pk_fma_f32 v[166:167], v[166:167], v[162:163], v[160:161]
	v_pk_fma_f32 v[168:169], v[168:169], v[162:163], v[160:161]
	v_pk_fma_f32 v[170:171], v[170:171], v[162:163], v[160:161]
	v_pk_mul_f32 v[164:165], v[164:165], v[84:85]
	v_pk_mul_f32 v[166:167], v[166:167], v[86:87]
	v_pk_mul_f32 v[168:169], v[168:169], v[80:81]
	v_pk_mul_f32 v[170:171], v[170:171], v[82:83]
	v_exp_f32_e32 v164, v164
	v_exp_f32_e32 v165, v165
	v_exp_f32_e32 v166, v166
	v_exp_f32_e32 v167, v167
	v_exp_f32_e32 v168, v168
	v_exp_f32_e32 v169, v169
	v_exp_f32_e32 v170, v170
	v_exp_f32_e32 v171, v171
	v_pk_add_f32 v[164:165], v[164:165], 1.0 op_sel_hi:[1,0]
	v_pk_add_f32 v[166:167], v[166:167], 1.0 op_sel_hi:[1,0]
	v_pk_add_f32 v[168:169], v[168:169], 1.0 op_sel_hi:[1,0]
	v_pk_add_f32 v[170:171], v[170:171], 1.0 op_sel_hi:[1,0]
	v_rcp_f32_e32 v164, v164
	v_rcp_f32_e32 v165, v165
	v_rcp_f32_e32 v166, v166
	v_rcp_f32_e32 v167, v167
	v_rcp_f32_e32 v168, v168
	v_rcp_f32_e32 v169, v169
	v_rcp_f32_e32 v170, v170
	v_rcp_f32_e32 v171, v171
	v_pk_mul_f32 v[84:85], v[84:85], v[164:165]
	v_pk_mul_f32 v[86:87], v[86:87], v[166:167]
	v_pk_mul_f32 v[80:81], v[80:81], v[168:169]
	v_pk_mul_f32 v[82:83], v[82:83], v[170:171]
	v_cvt_pk_bf16_f32 v84, v84, v85
	v_cvt_pk_bf16_f32 v85, v86, v87
	v_cvt_pk_bf16_f32 v86, v80, v81
	v_cvt_pk_bf16_f32 v87, v82, v83
; __device__ __forceinline__ unsigned cvt_pk_bf16(float lo, float hi) { unsigned r; asm volatile("v_cvt_pk_bf16_f32 %0, %1, %2" : "=v"(r) : "v"(lo), "v"(hi)); return r; }
; __device__ __forceinline__ float gelu_tanh_f(float y) { const float t = 0.7978845608028654f * (y + 0.044715f * y * y * y); return y * sigmoid_f(2.0f * t); }
; __device__ __forceinline__ float silu_f(float z) { return z / (1.0f + __expf(-z)); }
; __device__ __forceinline__ float sigmoid_f(float z) { return 1.0f / (1.0f + __expf(-z)); }
;     __device__ __forceinline__ void operator()(const AccT& acc, const Unit& u, int wr, int wc, int fr, int fq) const {
;     ...
;                 for (int bj = 0; bj < 2; ++bj) {
;                     const int nc = u.pn * 256 + bj * 128 + wc * 32 + 8 * fq, i = nc >> 4, s0 = nc & 15;
;                     const f32x4 v0 = acc[ai][bj][m][0], v1 = acc[ai][bj][m][1];
;                     u32x4 w; w.x = cvt_pk_bf16(gelu_tanh_f(v0[0]), gelu_tanh_f(v0[1])); w.y = cvt_pk_bf16(gelu_tanh_f(v0[2]), gelu_tanh_f(v0[3]));
;                     w.z = cvt_pk_bf16(gelu_tanh_f(v1[0]), gelu_tanh_f(v1[1])); w.w = cvt_pk_bf16(gelu_tanh_f(v1[2]), gelu_tanh_f(v1[3]));
;                     *(u32x4*)(YG + ((size_t)rg * 32 + i) * 1024 + u.g * 16 + s0) = w;
	global_store_dwordx4 v[180:181], v[84:87], off
	v_pk_mul_f32 v[164:165], v[76:77], v[76:77]
	v_pk_mul_f32 v[166:167], v[78:79], v[78:79]
	v_pk_mul_f32 v[168:169], v[72:73], v[72:73]
	v_pk_mul_f32 v[170:171], v[74:75], v[74:75]
	v_pk_fma_f32 v[164:165], v[164:165], v[162:163], v[160:161]
	v_pk_fma_f32 v[166:167], v[166:167], v[162:163], v[160:161]
	v_pk_fma_f32 v[168:169], v[168:169], v[162:163], v[160:161]
	v_pk_fma_f32 v[170:171], v[170:171], v[162:163], v[160:161]
	v_pk_mul_f32 v[164:165], v[164:165], v[76:77]
	v_pk_mul_f32 v[166:167], v[166:167], v[78:79]
	v_pk_mul_f32 v[168:169], v[168:169], v[72:73]
	v_pk_mul_f32 v[170:171], v[170:171], v[74:75]
	v_exp_f32_e32 v164, v164
	v_exp_f32_e32 v165, v165
	v_exp_f32_e32 v166, v166
	v_exp_f32_e32 v167, v167
	v_exp_f32_e32 v168, v168
	v_exp_f32_e32 v169, v169
	v_exp_f32_e32 v170, v170
	v_exp_f32_e32 v171, v171
	v_add_u32_e32 v176, s24, v148
	v_ashrrev_i32_e32 v177, 31, v176
	v_lshlrev_b64 v[176:177], 16, v[176:177]
	v_lshl_add_u64 v[178:179], v[176:177], 0, v[172:173]
	v_lshl_add_u64 v[180:181], v[176:177], 0, v[174:175]
	v_pk_add_f32 v[164:165], v[164:165], 1.0 op_sel_hi:[1,0]
	v_pk_add_f32 v[166:167], v[166:167], 1.0 op_sel_hi:[1,0]
	v_pk_add_f32 v[168:169], v[168:169], 1.0 op_sel_hi:[1,0]
	v_pk_add_f32 v[170:171], v[170:171], 1.0 op_sel_hi:[1,0]
	v_rcp_f32_e32 v164, v164
	v_rcp_f32_e32 v165, v165
	v_rcp_f32_e32 v166, v166
	v_rcp_f32_e32 v167, v167
	v_rcp_f32_e32 v168, v168
	v_rcp_f32_e32 v169, v169
	v_rcp_f32_e32 v170, v170
	v_rcp_f32_e32 v171, v171
	v_pk_mul_f32 v[76:77], v[76:77], v[164:165]
	v_pk_mul_f32 v[78:79], v[78:79], v[166:167]
	v_pk_mul_f32 v[72:73], v[72:73], v[168:169]
	v_pk_mul_f32 v[74:75], v[74:75], v[170:171]
	v_cvt_pk_bf16_f32 v76, v76, v77
	v_cvt_pk_bf16_f32 v77, v78, v79
	v_cvt_pk_bf16_f32 v78, v72, v73
	v_cvt_pk_bf16_f32 v79, v74, v75
	global_store_dwordx4 v[178:179], v[76:79], off
	v_pk_mul_f32 v[164:165], v[68:69], v[68:69]
	v_pk_mul_f32 v[166:167], v[70:71], v[70:71]
	v_pk_mul_f32 v[168:169], v[64:65], v[64:65]
	v_pk_mul_f32 v[170:171], v[66:67], v[66:67]
	v_pk_fma_f32 v[164:165], v[164:165], v[162:163], v[160:161]
	v_pk_fma_f32 v[166:167], v[166:167], v[162:163], v[160:161]
	v_pk_fma_f32 v[168:169], v[168:169], v[162:163], v[160:161]
	v_pk_fma_f32 v[170:171], v[170:171], v[162:163], v[160:161]
	v_pk_mul_f32 v[164:165], v[164:165], v[68:69]
	v_pk_mul_f32 v[166:167], v[166:167], v[70:71]
	v_pk_mul_f32 v[168:169], v[168:169], v[64:65]
	v_pk_mul_f32 v[170:171], v[170:171], v[66:67]
	v_exp_f32_e32 v164, v164
	v_exp_f32_e32 v165, v165
	v_exp_f32_e32 v166, v166
	v_exp_f32_e32 v167, v167
	v_exp_f32_e32 v168, v168
	v_exp_f32_e32 v169, v169
	v_exp_f32_e32 v170, v170
	v_exp_f32_e32 v171, v171
	v_pk_add_f32 v[164:165], v[164:165], 1.0 op_sel_hi:[1,0]
	v_pk_add_f32 v[166:167], v[166:167], 1.0 op_sel_hi:[1,0]
	v_pk_add_f32 v[168:169], v[168:169], 1.0 op_sel_hi:[1,0]
	v_pk_add_f32 v[170:171], v[170:171], 1.0 op_sel_hi:[1,0]
	v_rcp_f32_e32 v164, v164
	v_rcp_f32_e32 v165, v165
	v_rcp_f32_e32 v166, v166
	v_rcp_f32_e32 v167, v167
	v_rcp_f32_e32 v168, v168
	v_rcp_f32_e32 v169, v169
	v_rcp_f32_e32 v170, v170
	v_rcp_f32_e32 v171, v171
	v_pk_mul_f32 v[68:69], v[68:69], v[164:165]
	v_pk_mul_f32 v[70:71], v[70:71], v[166:167]
	v_pk_mul_f32 v[64:65], v[64:65], v[168:169]
	v_pk_mul_f32 v[66:67], v[66:67], v[170:171]
	v_cvt_pk_bf16_f32 v68, v68, v69
	v_cvt_pk_bf16_f32 v69, v70, v71
	v_cvt_pk_bf16_f32 v70, v64, v65
	v_cvt_pk_bf16_f32 v71, v66, v67
	global_store_dwordx4 v[180:181], v[68:71], off
	v_pk_mul_f32 v[164:165], v[60:61], v[60:61]
	v_pk_mul_f32 v[166:167], v[62:63], v[62:63]
	v_pk_mul_f32 v[168:169], v[56:57], v[56:57]
	v_pk_mul_f32 v[170:171], v[58:59], v[58:59]
	v_pk_fma_f32 v[164:165], v[164:165], v[162:163], v[160:161]
	v_pk_fma_f32 v[166:167], v[166:167], v[162:163], v[160:161]
	v_pk_fma_f32 v[168:169], v[168:169], v[162:163], v[160:161]
	v_pk_fma_f32 v[170:171], v[170:171], v[162:163], v[160:161]
	v_pk_mul_f32 v[164:165], v[164:165], v[60:61]
	v_pk_mul_f32 v[166:167], v[166:167], v[62:63]
	v_pk_mul_f32 v[168:169], v[168:169], v[56:57]
	v_pk_mul_f32 v[170:171], v[170:171], v[58:59]
	v_exp_f32_e32 v164, v164
	v_exp_f32_e32 v165, v165
	v_exp_f32_e32 v166, v166
	v_exp_f32_e32 v167, v167
	v_exp_f32_e32 v168, v168
	v_exp_f32_e32 v169, v169
	v_exp_f32_e32 v170, v170
	v_exp_f32_e32 v171, v171
	v_add_u32_e32 v176, s24, v149
	v_ashrrev_i32_e32 v177, 31, v176
	v_lshlrev_b64 v[176:177], 16, v[176:177]
	v_lshl_add_u64 v[178:179], v[176:177], 0, v[172:173]
	v_lshl_add_u64 v[180:181], v[176:177], 0, v[174:175]
	v_pk_add_f32 v[164:165], v[164:165], 1.0 op_sel_hi:[1,0]
	v_pk_add_f32 v[166:167], v[166:167], 1.0 op_sel_hi:[1,0]
	v_pk_add_f32 v[168:169], v[168:169], 1.0 op_sel_hi:[1,0]
	v_pk_add_f32 v[170:171], v[170:171], 1.0 op_sel_hi:[1,0]
	v_rcp_f32_e32 v164, v164
	v_rcp_f32_e32 v165, v165
	v_rcp_f32_e32 v166, v166
	v_rcp_f32_e32 v167, v167
	v_rcp_f32_e32 v168, v168
	v_rcp_f32_e32 v169, v169
	v_rcp_f32_e32 v170, v170
	v_rcp_f32_e32 v171, v171
	v_pk_mul_f32 v[60:61], v[60:61], v[164:165]
	v_pk_mul_f32 v[62:63], v[62:63], v[166:167]
	v_pk_mul_f32 v[56:57], v[56:57], v[168:169]
	v_pk_mul_f32 v[58:59], v[58:59], v[170:171]
	v_cvt_pk_bf16_f32 v60, v60, v61
	v_cvt_pk_bf16_f32 v61, v62, v63
	v_cvt_pk_bf16_f32 v62, v56, v57
	v_cvt_pk_bf16_f32 v63, v58, v59
	global_store_dwordx4 v[178:179], v[60:63], off
	v_pk_mul_f32 v[164:165], v[52:53], v[52:53]
	v_pk_mul_f32 v[166:167], v[54:55], v[54:55]
	v_pk_mul_f32 v[168:169], v[48:49], v[48:49]
	v_pk_mul_f32 v[170:171], v[50:51], v[50:51]
	v_pk_fma_f32 v[164:165], v[164:165], v[162:163], v[160:161]
	v_pk_fma_f32 v[166:167], v[166:167], v[162:163], v[160:161]
; __device__ __forceinline__ unsigned cvt_pk_bf16(float lo, float hi) { unsigned r; asm volatile("v_cvt_pk_bf16_f32 %0, %1, %2" : "=v"(r) : "v"(lo), "v"(hi)); return r; }
; __device__ __forceinline__ float gelu_tanh_f(float y) { const float t = 0.7978845608028654f * (y + 0.044715f * y * y * y); return y * sigmoid_f(2.0f * t); }
; __device__ __forceinline__ float silu_f(float z) { return z / (1.0f + __expf(-z)); }
; __device__ __forceinline__ float sigmoid_f(float z) { return 1.0f / (1.0f + __expf(-z)); }
;     __device__ __forceinline__ void operator()(const AccT& acc, const Unit& u, int wr, int wc, int fr, int fq) const {
;     ...
;                 for (int bj = 0; bj < 2; ++bj) {
;                     const int nc = u.pn * 256 + bj * 128 + wc * 32 + 8 * fq, i = nc >> 4, s0 = nc & 15;
;                     const f32x4 v0 = acc[ai][bj][m][0], v1 = acc[ai][bj][m][1];
;                     u32x4 w; w.x = cvt_pk_bf16(gelu_tanh_f(v0[0]), gelu_tanh_f(v0[1])); w.y = cvt_pk_bf16(gelu_tanh_f(v0[2]), gelu_tanh_f(v0[3]));
;                     w.z = cvt_pk_bf16(gelu_tanh_f(v1[0]), gelu_tanh_f(v1[1])); w.w = cvt_pk_bf16(gelu_tanh_f(v1[2]), gelu_tanh_f(v1[3]));
;                     *(u32x4*)(YG + ((size_t)rg * 32 + i) * 1024 + u.g * 16 + s0) = w;
	v_pk_fma_f32 v[168:169], v[168:169], v[162:163], v[160:161]
	v_pk_fma_f32 v[170:171], v[170:171], v[162:163], v[160:161]
	v_pk_mul_f32 v[164:165], v[164:165], v[52:53]
	v_pk_mul_f32 v[166:167], v[166:167], v[54:55]
	v_pk_mul_f32 v[168:169], v[168:169], v[48:49]
	v_pk_mul_f32 v[170:171], v[170:171], v[50:51]
	v_exp_f32_e32 v164, v164
	v_exp_f32_e32 v165, v165
	v_exp_f32_e32 v166, v166
	v_exp_f32_e32 v167, v167
	v_exp_f32_e32 v168, v168
	v_exp_f32_e32 v169, v169
	v_exp_f32_e32 v170, v170
	v_exp_f32_e32 v171, v171
	v_pk_add_f32 v[164:165], v[164:165], 1.0 op_sel_hi:[1,0]
	v_pk_add_f32 v[166:167], v[166:167], 1.0 op_sel_hi:[1,0]
	v_pk_add_f32 v[168:169], v[168:169], 1.0 op_sel_hi:[1,0]
	v_pk_add_f32 v[170:171], v[170:171], 1.0 op_sel_hi:[1,0]
	v_rcp_f32_e32 v164, v164
	v_rcp_f32_e32 v165, v165
	v_rcp_f32_e32 v166, v166
	v_rcp_f32_e32 v167, v167
	v_rcp_f32_e32 v168, v168
	v_rcp_f32_e32 v169, v169
	v_rcp_f32_e32 v170, v170
	v_rcp_f32_e32 v171, v171
	v_pk_mul_f32 v[52:53], v[52:53], v[164:165]
	v_pk_mul_f32 v[54:55], v[54:55], v[166:167]
	v_pk_mul_f32 v[48:49], v[48:49], v[168:169]
	v_pk_mul_f32 v[50:51], v[50:51], v[170:171]
	v_cvt_pk_bf16_f32 v52, v52, v53
	v_cvt_pk_bf16_f32 v53, v54, v55
	v_cvt_pk_bf16_f32 v54, v48, v49
	v_cvt_pk_bf16_f32 v55, v50, v51
	global_store_dwordx4 v[180:181], v[52:55], off
	v_pk_mul_f32 v[164:165], v[44:45], v[44:45]
	v_pk_mul_f32 v[166:167], v[46:47], v[46:47]
	v_pk_mul_f32 v[168:169], v[40:41], v[40:41]
	v_pk_mul_f32 v[170:171], v[42:43], v[42:43]
	v_pk_fma_f32 v[164:165], v[164:165], v[162:163], v[160:161]
	v_pk_fma_f32 v[166:167], v[166:167], v[162:163], v[160:161]
	v_pk_fma_f32 v[168:169], v[168:169], v[162:163], v[160:161]
	v_pk_fma_f32 v[170:171], v[170:171], v[162:163], v[160:161]
	v_pk_mul_f32 v[164:165], v[164:165], v[44:45]
	v_pk_mul_f32 v[166:167], v[166:167], v[46:47]
	v_pk_mul_f32 v[168:169], v[168:169], v[40:41]
	v_pk_mul_f32 v[170:171], v[170:171], v[42:43]
	v_exp_f32_e32 v164, v164
	v_exp_f32_e32 v165, v165
	v_exp_f32_e32 v166, v166
	v_exp_f32_e32 v167, v167
	v_exp_f32_e32 v168, v168
	v_exp_f32_e32 v169, v169
	v_exp_f32_e32 v170, v170
	v_exp_f32_e32 v171, v171
	v_add_u32_e32 v176, s24, v150
	v_ashrrev_i32_e32 v177, 31, v176
	v_lshlrev_b64 v[176:177], 16, v[176:177]
	v_lshl_add_u64 v[178:179], v[176:177], 0, v[172:173]
	v_lshl_add_u64 v[180:181], v[176:177], 0, v[174:175]
	v_pk_add_f32 v[164:165], v[164:165], 1.0 op_sel_hi:[1,0]
	v_pk_add_f32 v[166:167], v[166:167], 1.0 op_sel_hi:[1,0]
	v_pk_add_f32 v[168:169], v[168:169], 1.0 op_sel_hi:[1,0]
	v_pk_add_f32 v[170:171], v[170:171], 1.0 op_sel_hi:[1,0]
	v_rcp_f32_e32 v164, v164
	v_rcp_f32_e32 v165, v165
	v_rcp_f32_e32 v166, v166
	v_rcp_f32_e32 v167, v167
	v_rcp_f32_e32 v168, v168
	v_rcp_f32_e32 v169, v169
	v_rcp_f32_e32 v170, v170
	v_rcp_f32_e32 v171, v171
	v_pk_mul_f32 v[44:45], v[44:45], v[164:165]
	v_pk_mul_f32 v[46:47], v[46:47], v[166:167]
	v_pk_mul_f32 v[40:41], v[40:41], v[168:169]
	v_pk_mul_f32 v[42:43], v[42:43], v[170:171]
	v_cvt_pk_bf16_f32 v44, v44, v45
	v_cvt_pk_bf16_f32 v45, v46, v47
	v_cvt_pk_bf16_f32 v46, v40, v41
	v_cvt_pk_bf16_f32 v47, v42, v43
	global_store_dwordx4 v[178:179], v[44:47], off
	v_pk_mul_f32 v[164:165], v[36:37], v[36:37]
	v_pk_mul_f32 v[166:167], v[38:39], v[38:39]
	v_pk_mul_f32 v[168:169], v[32:33], v[32:33]
	v_pk_mul_f32 v[170:171], v[34:35], v[34:35]
	v_pk_fma_f32 v[164:165], v[164:165], v[162:163], v[160:161]
	v_pk_fma_f32 v[166:167], v[166:167], v[162:163], v[160:161]
	v_pk_fma_f32 v[168:169], v[168:169], v[162:163], v[160:161]
	v_pk_fma_f32 v[170:171], v[170:171], v[162:163], v[160:161]
	v_pk_mul_f32 v[164:165], v[164:165], v[36:37]
	v_pk_mul_f32 v[166:167], v[166:167], v[38:39]
	v_pk_mul_f32 v[168:169], v[168:169], v[32:33]
	v_pk_mul_f32 v[170:171], v[170:171], v[34:35]
	v_exp_f32_e32 v164, v164
	v_exp_f32_e32 v165, v165
	v_exp_f32_e32 v166, v166
	v_exp_f32_e32 v167, v167
	v_exp_f32_e32 v168, v168
	v_exp_f32_e32 v169, v169
	v_exp_f32_e32 v170, v170
	v_exp_f32_e32 v171, v171
	v_pk_add_f32 v[164:165], v[164:165], 1.0 op_sel_hi:[1,0]
	v_pk_add_f32 v[166:167], v[166:167], 1.0 op_sel_hi:[1,0]
	v_pk_add_f32 v[168:169], v[168:169], 1.0 op_sel_hi:[1,0]
	v_pk_add_f32 v[170:171], v[170:171], 1.0 op_sel_hi:[1,0]
	v_rcp_f32_e32 v164, v164
	v_rcp_f32_e32 v165, v165
	v_rcp_f32_e32 v166, v166
	v_rcp_f32_e32 v167, v167
	v_rcp_f32_e32 v168, v168
	v_rcp_f32_e32 v169, v169
	v_rcp_f32_e32 v170, v170
	v_rcp_f32_e32 v171, v171
	v_pk_mul_f32 v[36:37], v[36:37], v[164:165]
	v_pk_mul_f32 v[38:39], v[38:39], v[166:167]
	v_pk_mul_f32 v[32:33], v[32:33], v[168:169]
	v_pk_mul_f32 v[34:35], v[34:35], v[170:171]
	v_cvt_pk_bf16_f32 v36, v36, v37
	v_cvt_pk_bf16_f32 v37, v38, v39
	v_cvt_pk_bf16_f32 v38, v32, v33
	v_cvt_pk_bf16_f32 v39, v34, v35
	global_store_dwordx4 v[180:181], v[36:39], off
	v_pk_mul_f32 v[164:165], v[28:29], v[28:29]
	v_pk_mul_f32 v[166:167], v[30:31], v[30:31]
	v_pk_mul_f32 v[168:169], v[24:25], v[24:25]
	v_pk_mul_f32 v[170:171], v[26:27], v[26:27]
	v_pk_fma_f32 v[164:165], v[164:165], v[162:163], v[160:161]
	v_pk_fma_f32 v[166:167], v[166:167], v[162:163], v[160:161]
	v_pk_fma_f32 v[168:169], v[168:169], v[162:163], v[160:161]
	v_pk_fma_f32 v[170:171], v[170:171], v[162:163], v[160:161]
	v_pk_mul_f32 v[164:165], v[164:165], v[28:29]
	v_pk_mul_f32 v[166:167], v[166:167], v[30:31]
	v_pk_mul_f32 v[168:169], v[168:169], v[24:25]
	v_pk_mul_f32 v[170:171], v[170:171], v[26:27]
	v_exp_f32_e32 v164, v164
	v_exp_f32_e32 v165, v165
	v_exp_f32_e32 v166, v166
	v_exp_f32_e32 v167, v167
	v_exp_f32_e32 v168, v168
	v_exp_f32_e32 v169, v169
	v_exp_f32_e32 v170, v170
	v_exp_f32_e32 v171, v171
	v_add_u32_e32 v176, s24, v151
; __device__ __forceinline__ unsigned cvt_pk_bf16(float lo, float hi) { unsigned r; asm volatile("v_cvt_pk_bf16_f32 %0, %1, %2" : "=v"(r) : "v"(lo), "v"(hi)); return r; }
; __device__ __forceinline__ float gelu_tanh_f(float y) { const float t = 0.7978845608028654f * (y + 0.044715f * y * y * y); return y * sigmoid_f(2.0f * t); }
; __device__ __forceinline__ float silu_f(float z) { return z / (1.0f + __expf(-z)); }
; __device__ __forceinline__ float sigmoid_f(float z) { return 1.0f / (1.0f + __expf(-z)); }
;     __device__ __forceinline__ void operator()(const AccT& acc, const Unit& u, int wr, int wc, int fr, int fq) const {
;     ...
;                 for (int bj = 0; bj < 2; ++bj) {
;                     const int nc = u.pn * 256 + bj * 128 + wc * 32 + 8 * fq, i = nc >> 4, s0 = nc & 15;
;                     const f32x4 v0 = acc[ai][bj][m][0], v1 = acc[ai][bj][m][1];
;                     u32x4 w; w.x = cvt_pk_bf16(gelu_tanh_f(v0[0]), gelu_tanh_f(v0[1])); w.y = cvt_pk_bf16(gelu_tanh_f(v0[2]), gelu_tanh_f(v0[3]));
;                     w.z = cvt_pk_bf16(gelu_tanh_f(v1[0]), gelu_tanh_f(v1[1])); w.w = cvt_pk_bf16(gelu_tanh_f(v1[2]), gelu_tanh_f(v1[3]));
;                     *(u32x4*)(YG + ((size_t)rg * 32 + i) * 1024 + u.g * 16 + s0) = w;
	v_ashrrev_i32_e32 v177, 31, v176
	v_lshlrev_b64 v[176:177], 16, v[176:177]
	v_lshl_add_u64 v[178:179], v[176:177], 0, v[172:173]
	v_lshl_add_u64 v[180:181], v[176:177], 0, v[174:175]
	v_pk_add_f32 v[164:165], v[164:165], 1.0 op_sel_hi:[1,0]
	v_pk_add_f32 v[166:167], v[166:167], 1.0 op_sel_hi:[1,0]
	v_pk_add_f32 v[168:169], v[168:169], 1.0 op_sel_hi:[1,0]
	v_pk_add_f32 v[170:171], v[170:171], 1.0 op_sel_hi:[1,0]
	v_rcp_f32_e32 v164, v164
	v_rcp_f32_e32 v165, v165
	v_rcp_f32_e32 v166, v166
	v_rcp_f32_e32 v167, v167
	v_rcp_f32_e32 v168, v168
	v_rcp_f32_e32 v169, v169
	v_rcp_f32_e32 v170, v170
	v_rcp_f32_e32 v171, v171
	v_pk_mul_f32 v[28:29], v[28:29], v[164:165]
	v_pk_mul_f32 v[30:31], v[30:31], v[166:167]
	v_pk_mul_f32 v[24:25], v[24:25], v[168:169]
	v_pk_mul_f32 v[26:27], v[26:27], v[170:171]
	v_cvt_pk_bf16_f32 v28, v28, v29
	v_cvt_pk_bf16_f32 v29, v30, v31
	v_cvt_pk_bf16_f32 v30, v24, v25
	v_cvt_pk_bf16_f32 v31, v26, v27
	global_store_dwordx4 v[178:179], v[28:31], off
	v_pk_mul_f32 v[164:165], v[20:21], v[20:21]
	v_pk_mul_f32 v[166:167], v[22:23], v[22:23]
	v_pk_mul_f32 v[168:169], v[16:17], v[16:17]
	v_pk_mul_f32 v[170:171], v[18:19], v[18:19]
	v_pk_fma_f32 v[164:165], v[164:165], v[162:163], v[160:161]
	v_pk_fma_f32 v[166:167], v[166:167], v[162:163], v[160:161]
	v_pk_fma_f32 v[168:169], v[168:169], v[162:163], v[160:161]
	v_pk_fma_f32 v[170:171], v[170:171], v[162:163], v[160:161]
	v_pk_mul_f32 v[164:165], v[164:165], v[20:21]
	v_pk_mul_f32 v[166:167], v[166:167], v[22:23]
	v_pk_mul_f32 v[168:169], v[168:169], v[16:17]
	v_pk_mul_f32 v[170:171], v[170:171], v[18:19]
	v_exp_f32_e32 v164, v164
	v_exp_f32_e32 v165, v165
	v_exp_f32_e32 v166, v166
	v_exp_f32_e32 v167, v167
	v_exp_f32_e32 v168, v168
	v_exp_f32_e32 v169, v169
	v_exp_f32_e32 v170, v170
	v_exp_f32_e32 v171, v171
	v_pk_add_f32 v[164:165], v[164:165], 1.0 op_sel_hi:[1,0]
	v_pk_add_f32 v[166:167], v[166:167], 1.0 op_sel_hi:[1,0]
	v_pk_add_f32 v[168:169], v[168:169], 1.0 op_sel_hi:[1,0]
	v_pk_add_f32 v[170:171], v[170:171], 1.0 op_sel_hi:[1,0]
	v_rcp_f32_e32 v164, v164
	v_rcp_f32_e32 v165, v165
	v_rcp_f32_e32 v166, v166
	v_rcp_f32_e32 v167, v167
	v_rcp_f32_e32 v168, v168
	v_rcp_f32_e32 v169, v169
	v_rcp_f32_e32 v170, v170
	v_rcp_f32_e32 v171, v171
	v_pk_mul_f32 v[20:21], v[20:21], v[164:165]
	v_pk_mul_f32 v[22:23], v[22:23], v[166:167]
	v_pk_mul_f32 v[16:17], v[16:17], v[168:169]
	v_pk_mul_f32 v[18:19], v[18:19], v[170:171]
	v_cvt_pk_bf16_f32 v20, v20, v21
	v_cvt_pk_bf16_f32 v21, v22, v23
	v_cvt_pk_bf16_f32 v22, v16, v17
	v_cvt_pk_bf16_f32 v23, v18, v19
	global_store_dwordx4 v[180:181], v[20:23], off
	v_pk_mul_f32 v[164:165], v[12:13], v[12:13]
	v_pk_mul_f32 v[166:167], v[14:15], v[14:15]
	v_pk_mul_f32 v[168:169], v[8:9], v[8:9]
	v_pk_mul_f32 v[170:171], v[10:11], v[10:11]
	v_pk_fma_f32 v[164:165], v[164:165], v[162:163], v[160:161]
	v_pk_fma_f32 v[166:167], v[166:167], v[162:163], v[160:161]
	v_pk_fma_f32 v[168:169], v[168:169], v[162:163], v[160:161]
	v_pk_fma_f32 v[170:171], v[170:171], v[162:163], v[160:161]
	v_pk_mul_f32 v[164:165], v[164:165], v[12:13]
	v_pk_mul_f32 v[166:167], v[166:167], v[14:15]
	v_pk_mul_f32 v[168:169], v[168:169], v[8:9]
	v_pk_mul_f32 v[170:171], v[170:171], v[10:11]
	v_exp_f32_e32 v164, v164
	v_exp_f32_e32 v165, v165
	v_exp_f32_e32 v166, v166
	v_exp_f32_e32 v167, v167
	v_exp_f32_e32 v168, v168
	v_exp_f32_e32 v169, v169
	v_exp_f32_e32 v170, v170
	v_exp_f32_e32 v171, v171
	v_add_u32_e32 v176, s24, v152
	v_ashrrev_i32_e32 v177, 31, v176
	v_lshlrev_b64 v[176:177], 16, v[176:177]
	v_lshl_add_u64 v[178:179], v[176:177], 0, v[172:173]
	v_lshl_add_u64 v[180:181], v[176:177], 0, v[174:175]
	v_pk_add_f32 v[164:165], v[164:165], 1.0 op_sel_hi:[1,0]
	v_pk_add_f32 v[166:167], v[166:167], 1.0 op_sel_hi:[1,0]
	v_pk_add_f32 v[168:169], v[168:169], 1.0 op_sel_hi:[1,0]
	v_pk_add_f32 v[170:171], v[170:171], 1.0 op_sel_hi:[1,0]
	v_rcp_f32_e32 v164, v164
	v_rcp_f32_e32 v165, v165
	v_rcp_f32_e32 v166, v166
	v_rcp_f32_e32 v167, v167
	v_rcp_f32_e32 v168, v168
	v_rcp_f32_e32 v169, v169
	v_rcp_f32_e32 v170, v170
	v_rcp_f32_e32 v171, v171
	v_pk_mul_f32 v[12:13], v[12:13], v[164:165]
	v_pk_mul_f32 v[14:15], v[14:15], v[166:167]
	v_pk_mul_f32 v[8:9], v[8:9], v[168:169]
	v_pk_mul_f32 v[10:11], v[10:11], v[170:171]
	v_cvt_pk_bf16_f32 v12, v12, v13
	v_cvt_pk_bf16_f32 v13, v14, v15
	v_cvt_pk_bf16_f32 v14, v8, v9
	v_cvt_pk_bf16_f32 v15, v10, v11
	global_store_dwordx4 v[178:179], v[12:15], off
	v_pk_mul_f32 v[164:165], v[4:5], v[4:5]
	v_pk_mul_f32 v[166:167], v[6:7], v[6:7]
	v_pk_mul_f32 v[168:169], v[0:1], v[0:1]
	v_pk_mul_f32 v[170:171], v[2:3], v[2:3]
	v_pk_fma_f32 v[164:165], v[164:165], v[162:163], v[160:161]
	v_pk_fma_f32 v[166:167], v[166:167], v[162:163], v[160:161]
	v_pk_fma_f32 v[168:169], v[168:169], v[162:163], v[160:161]
	v_pk_fma_f32 v[170:171], v[170:171], v[162:163], v[160:161]
	v_pk_mul_f32 v[164:165], v[164:165], v[4:5]
	v_pk_mul_f32 v[166:167], v[166:167], v[6:7]
	v_pk_mul_f32 v[168:169], v[168:169], v[0:1]
	v_pk_mul_f32 v[170:171], v[170:171], v[2:3]
	v_exp_f32_e32 v164, v164
	v_exp_f32_e32 v165, v165
	v_exp_f32_e32 v166, v166
	v_exp_f32_e32 v167, v167
	v_exp_f32_e32 v168, v168
	v_exp_f32_e32 v169, v169
	v_exp_f32_e32 v170, v170
	v_exp_f32_e32 v171, v171
	v_pk_add_f32 v[164:165], v[164:165], 1.0 op_sel_hi:[1,0]
	v_pk_add_f32 v[166:167], v[166:167], 1.0 op_sel_hi:[1,0]
	v_pk_add_f32 v[168:169], v[168:169], 1.0 op_sel_hi:[1,0]
	v_pk_add_f32 v[170:171], v[170:171], 1.0 op_sel_hi:[1,0]
	v_rcp_f32_e32 v164, v164
	v_rcp_f32_e32 v165, v165
	v_rcp_f32_e32 v166, v166
	v_rcp_f32_e32 v167, v167
	v_rcp_f32_e32 v168, v168
	v_rcp_f32_e32 v169, v169
	v_rcp_f32_e32 v170, v170
	v_rcp_f32_e32 v171, v171
	v_pk_mul_f32 v[4:5], v[4:5], v[164:165]
	v_pk_mul_f32 v[6:7], v[6:7], v[166:167]
	v_pk_mul_f32 v[0:1], v[0:1], v[168:169]
	v_pk_mul_f32 v[2:3], v[2:3], v[170:171]
	v_cvt_pk_bf16_f32 v4, v4, v5
	v_cvt_pk_bf16_f32 v5, v6, v7
	v_cvt_pk_bf16_f32 v6, v0, v1
	v_cvt_pk_bf16_f32 v7, v2, v3
	s_mov_b64 s[22:23], -1
	s_andn2_b64 vcc, exec, s[4:5]
	global_store_dwordx4 v[180:181], v[4:7], off
	s_cbranch_vccnz .LBB0_530
	s_andn2_b64 vcc, exec, s[6:7]
	s_cbranch_vccnz .LBB0_529
	s_barrier
	s_branch .LBB0_529
